# weight prefetch at all 17 seams that precede a GEMM phase
# speedup vs baseline: 1.0097x; 1.0097x over previous
.LBB0_170:
	s_cmp_lt_u32 s85, 4
	s_barrier
	s_cbranch_scc1 .LBB0_224
	s_waitcnt vmcnt(0)
	s_barrier
	v_readlane_b32 s98, v250, 21
	s_nop 3
	s_cmp_eq_u32 s98, 0
	s_cbranch_scc1 .Lpf_skip_3
	s_mul_i32 s99, s33, 7
	s_add_i32 s99, s99, s98
	s_add_i32 s99, s99, -1
	s_mul_i32 s99, s99, 0x2000
	v_lshlrev_b32_e32 v251, 7, v178
	v_add_u32_e32 v251, s99, v251
	s_add_u32 s100, s88, 0xd00000
	s_addc_u32 s101, s89, 0
	global_load_dword v252, v251, s[100:101]
